# row-scale table: generic scan kept (no grid-size assumption), rows 0/1 built concurrently; all previous edits
# speedup vs baseline: 1.0067x; 1.0067x over previous
.LBB0_207:
	s_add_u32 s8, s28, 0x5800000
	s_movk_i32 s0, 0x100
	s_addc_u32 s9, s29, 0
	v_cmp_gt_u32_e64 s[4:5], s0, v197
	s_add_i32 s0, 0, 0x20000
	s_cmp_gt_i32 s50, -1
	v_lshl_add_u32 v0, v197, 2, s0
	s_cselect_b64 s[0:1], -1, 0
	s_and_b64 s[0:1], s[0:1], s[4:5]
	s_cmp_gt_i32 s52, -1
	s_cselect_b64 s[10:11], -1, 0
	s_andn2_b64 s[10:11], s[10:11], s[4:5]
	s_or_b64 s[0:1], s[0:1], s[10:11]
	s_waitcnt lgkmcnt(0)
	s_barrier
	s_and_saveexec_b64 s[10:11], s[0:1]
	s_cbranch_execz .LBB0_209
	v_mov_b32_e32 v30, s50
	v_mov_b32_e32 v31, s52
	v_cmp_lt_u32_e32 vcc, 0xff, v197
	v_and_b32_e32 v2, 0xff, v197
	s_nop 0
	v_cndmask_b32_e32 v30, v30, v31, vcc
	v_lshl_or_b32 v2, v30, 8, v2
	v_mov_b32_e32 v3, 0
	v_add_u32_e32 v18, 0x38000, v2
	v_mov_b32_e32 v19, v3
	v_lshl_add_u64 v[4:5], v[2:3], 2, s[8:9]
	v_add_u32_e32 v6, 0x8000, v2
	v_mov_b32_e32 v7, v3
	v_add_u32_e32 v8, 0x10000, v2
	v_mov_b32_e32 v9, v3
	v_add_u32_e32 v10, 0x18000, v2
	v_mov_b32_e32 v11, v3
	v_add_u32_e32 v12, 0x20000, v2
	v_mov_b32_e32 v13, v3
	v_add_u32_e32 v14, 0x28000, v2
	v_mov_b32_e32 v15, v3
	v_add_u32_e32 v16, 0x30000, v2
	v_mov_b32_e32 v17, v3
	v_lshl_add_u64 v[18:19], v[18:19], 2, s[8:9]
	v_lshl_add_u64 v[6:7], v[6:7], 2, s[8:9]
	v_lshl_add_u64 v[8:9], v[8:9], 2, s[8:9]
	v_lshl_add_u64 v[10:11], v[10:11], 2, s[8:9]
	v_lshl_add_u64 v[12:13], v[12:13], 2, s[8:9]
	v_lshl_add_u64 v[14:15], v[14:15], 2, s[8:9]
	v_lshl_add_u64 v[16:17], v[16:17], 2, s[8:9]
	global_load_dword v1, v[4:5], off
	global_load_dword v20, v[6:7], off
	global_load_dword v21, v[8:9], off
	global_load_dword v22, v[10:11], off
	global_load_dword v23, v[12:13], off
	global_load_dword v24, v[14:15], off
	global_load_dword v25, v[16:17], off
	s_nop 0
	global_load_dword v18, v[18:19], off
	v_add_u32_e32 v4, 0x40000, v2
	v_mov_b32_e32 v5, v3
	v_add_u32_e32 v6, 0x48000, v2
	v_mov_b32_e32 v7, v3
	v_add_u32_e32 v8, 0x50000, v2
	v_mov_b32_e32 v9, v3
	v_add_u32_e32 v10, 0x58000, v2
	v_mov_b32_e32 v11, v3
	v_add_u32_e32 v12, 0x60000, v2
	v_add_u32_e32 v14, 0x68000, v2
	v_add_u32_e32 v16, 0x70000, v2
	v_add_u32_e32 v2, 0x78000, v2
	v_lshl_add_u64 v[4:5], v[4:5], 2, s[8:9]
	v_lshl_add_u64 v[6:7], v[6:7], 2, s[8:9]
	v_lshl_add_u64 v[8:9], v[8:9], 2, s[8:9]
	v_lshl_add_u64 v[10:11], v[10:11], 2, s[8:9]
	v_mov_b32_e32 v13, v3
	v_mov_b32_e32 v15, v3
	v_mov_b32_e32 v17, v3
	v_lshl_add_u64 v[2:3], v[2:3], 2, s[8:9]
	v_lshl_add_u64 v[12:13], v[12:13], 2, s[8:9]
	v_lshl_add_u64 v[14:15], v[14:15], 2, s[8:9]
	v_lshl_add_u64 v[16:17], v[16:17], 2, s[8:9]
	global_load_dword v4, v[4:5], off
	s_nop 0
	global_load_dword v5, v[6:7], off
	s_nop 0
	global_load_dword v6, v[8:9], off
	global_load_dword v7, v[10:11], off
	s_nop 0
	global_load_dword v8, v[12:13], off
	global_load_dword v9, v[14:15], off
	global_load_dword v10, v[16:17], off
	s_nop 0
	global_load_dword v2, v[2:3], off
	v_mov_b32_e32 v3, 0x358637bd
	s_mov_b32 s0, 0xf800000
	s_waitcnt vmcnt(15)
	v_add_f32_e32 v1, 0, v1
	s_waitcnt vmcnt(14)
	v_add_f32_e32 v1, v1, v20
	s_waitcnt vmcnt(13)
	v_add_f32_e32 v1, v1, v21
	s_waitcnt vmcnt(12)
	v_add_f32_e32 v1, v1, v22
	s_waitcnt vmcnt(11)
	v_add_f32_e32 v1, v1, v23
	s_waitcnt vmcnt(10)
	v_add_f32_e32 v1, v1, v24
	s_waitcnt vmcnt(9)
	v_add_f32_e32 v1, v1, v25
	s_waitcnt vmcnt(8)
	v_add_f32_e32 v1, v1, v18
	s_waitcnt vmcnt(7)
	v_add_f32_e32 v1, v1, v4
	s_waitcnt vmcnt(6)
	v_add_f32_e32 v1, v1, v5
	s_waitcnt vmcnt(5)
	v_add_f32_e32 v1, v1, v6
	s_waitcnt vmcnt(4)
	v_add_f32_e32 v1, v1, v7
	s_waitcnt vmcnt(3)
	v_add_f32_e32 v1, v1, v8
	s_waitcnt vmcnt(2)
	v_add_f32_e32 v1, v1, v9
	s_waitcnt vmcnt(1)
	v_add_f32_e32 v1, v1, v10
	s_waitcnt vmcnt(0)
	v_add_f32_e32 v1, v1, v2
	v_fmac_f32_e32 v3, 0x3a800000, v1
	v_mul_f32_e32 v1, 0x4f800000, v3
	v_cmp_gt_f32_e32 vcc, s0, v3
	s_nop 1
	v_cndmask_b32_e32 v1, v3, v1, vcc
	v_sqrt_f32_e32 v2, v1
	v_mov_b32_e32 v3, 0x260
	v_add_u32_e32 v4, -1, v2
	v_add_u32_e32 v5, 1, v2
	v_fma_f32 v6, -v4, v2, v1
	v_fma_f32 v7, -v5, v2, v1
	v_cmp_ge_f32_e64 s[0:1], 0, v6
	s_nop 1
	v_cndmask_b32_e64 v2, v2, v4, s[0:1]
	v_cmp_lt_f32_e64 s[0:1], 0, v7
	s_nop 1
	v_cndmask_b32_e64 v2, v2, v5, s[0:1]
	v_mul_f32_e32 v4, 0x37800000, v2
	v_cndmask_b32_e32 v2, v2, v4, vcc
	v_cmp_class_f32_e32 vcc, v1, v3
	s_nop 1
	v_cndmask_b32_e32 v1, v2, v1, vcc
	v_div_scale_f32 v2, s[0:1], v1, v1, 1.0
	v_rcp_f32_e32 v3, v2
	v_div_scale_f32 v4, vcc, 1.0, v1, 1.0
	v_fma_f32 v5, -v2, v3, 1.0
	v_fmac_f32_e32 v3, v5, v3
	v_mul_f32_e32 v5, v4, v3
	v_fma_f32 v6, -v2, v5, v4
	v_fmac_f32_e32 v5, v6, v3
	v_fma_f32 v2, -v2, v5, v4
	v_div_fmas_f32 v2, v2, v3, v5
	v_div_fixup_f32 v1, v2, v1, 1.0
	ds_write_b32 v0, v1

.LBB0_397:
	s_add_u32 s8, s28, 0x5a00000
	s_movk_i32 s0, 0x100
	s_addc_u32 s9, s29, 0
	v_cmp_gt_u32_e64 s[4:5], s0, v197
	s_add_i32 s0, 0, 0x20000
	s_cmp_gt_i32 s58, -1
	v_lshl_add_u32 v0, v197, 2, s0
	s_cselect_b64 s[0:1], -1, 0
	s_and_b64 s[0:1], s[0:1], s[4:5]
	s_cmp_gt_i32 s60, -1
	s_cselect_b64 s[10:11], -1, 0
	s_andn2_b64 s[10:11], s[10:11], s[4:5]
	s_or_b64 s[0:1], s[0:1], s[10:11]
	s_waitcnt vmcnt(0)
	s_barrier
	s_and_saveexec_b64 s[10:11], s[0:1]
	s_cbranch_execz .LBB0_399
	v_mov_b32_e32 v30, s58
	v_mov_b32_e32 v31, s60
	v_cmp_lt_u32_e32 vcc, 0xff, v197
	v_and_b32_e32 v2, 0xff, v197
	s_nop 0
	v_cndmask_b32_e32 v30, v30, v31, vcc
	v_lshl_or_b32 v2, v30, 8, v2
	v_mov_b32_e32 v3, 0
	v_add_u32_e32 v18, 0x38000, v2
	v_mov_b32_e32 v19, v3
	v_lshl_add_u64 v[4:5], v[2:3], 2, s[8:9]
	v_add_u32_e32 v6, 0x8000, v2
	v_mov_b32_e32 v7, v3
	v_add_u32_e32 v8, 0x10000, v2
	v_mov_b32_e32 v9, v3
	v_add_u32_e32 v10, 0x18000, v2
	v_mov_b32_e32 v11, v3
	v_add_u32_e32 v12, 0x20000, v2
	v_mov_b32_e32 v13, v3
	v_add_u32_e32 v14, 0x28000, v2
	v_mov_b32_e32 v15, v3
	v_add_u32_e32 v16, 0x30000, v2
	v_mov_b32_e32 v17, v3
	v_lshl_add_u64 v[18:19], v[18:19], 2, s[8:9]
	v_lshl_add_u64 v[6:7], v[6:7], 2, s[8:9]
	v_lshl_add_u64 v[8:9], v[8:9], 2, s[8:9]
	v_lshl_add_u64 v[10:11], v[10:11], 2, s[8:9]
	v_lshl_add_u64 v[12:13], v[12:13], 2, s[8:9]
	v_lshl_add_u64 v[14:15], v[14:15], 2, s[8:9]
	v_lshl_add_u64 v[16:17], v[16:17], 2, s[8:9]
	global_load_dword v1, v[4:5], off
	global_load_dword v20, v[6:7], off
	global_load_dword v21, v[8:9], off
	global_load_dword v22, v[10:11], off
	global_load_dword v23, v[12:13], off
	global_load_dword v24, v[14:15], off
	global_load_dword v25, v[16:17], off
	s_nop 0
	global_load_dword v18, v[18:19], off
	v_add_u32_e32 v4, 0x40000, v2
	v_mov_b32_e32 v5, v3
	v_add_u32_e32 v6, 0x48000, v2
	v_mov_b32_e32 v7, v3
	v_add_u32_e32 v8, 0x50000, v2
	v_mov_b32_e32 v9, v3
	v_add_u32_e32 v10, 0x58000, v2
	v_mov_b32_e32 v11, v3
	v_add_u32_e32 v12, 0x60000, v2
	v_add_u32_e32 v14, 0x68000, v2
	v_add_u32_e32 v16, 0x70000, v2
	v_add_u32_e32 v2, 0x78000, v2
	v_lshl_add_u64 v[4:5], v[4:5], 2, s[8:9]
	v_lshl_add_u64 v[6:7], v[6:7], 2, s[8:9]
	v_lshl_add_u64 v[8:9], v[8:9], 2, s[8:9]
	v_lshl_add_u64 v[10:11], v[10:11], 2, s[8:9]
	v_mov_b32_e32 v13, v3
	v_mov_b32_e32 v15, v3
	v_mov_b32_e32 v17, v3
	v_lshl_add_u64 v[2:3], v[2:3], 2, s[8:9]
	v_lshl_add_u64 v[12:13], v[12:13], 2, s[8:9]
	v_lshl_add_u64 v[14:15], v[14:15], 2, s[8:9]
	v_lshl_add_u64 v[16:17], v[16:17], 2, s[8:9]
	global_load_dword v4, v[4:5], off
	s_nop 0
	global_load_dword v5, v[6:7], off
	s_nop 0
	global_load_dword v6, v[8:9], off
	global_load_dword v7, v[10:11], off
	s_nop 0
	global_load_dword v8, v[12:13], off
	global_load_dword v9, v[14:15], off
	global_load_dword v10, v[16:17], off
	s_nop 0
	global_load_dword v2, v[2:3], off
	v_mov_b32_e32 v3, 0x358637bd
	s_mov_b32 s0, 0xf800000
	s_waitcnt vmcnt(15)
	v_add_f32_e32 v1, 0, v1
	s_waitcnt vmcnt(14)
	v_add_f32_e32 v1, v1, v20
	s_waitcnt vmcnt(13)
	v_add_f32_e32 v1, v1, v21
	s_waitcnt vmcnt(12)
	v_add_f32_e32 v1, v1, v22
	s_waitcnt vmcnt(11)
	v_add_f32_e32 v1, v1, v23
	s_waitcnt vmcnt(10)
	v_add_f32_e32 v1, v1, v24
	s_waitcnt vmcnt(9)
	v_add_f32_e32 v1, v1, v25
	s_waitcnt vmcnt(8)
	v_add_f32_e32 v1, v1, v18
	s_waitcnt vmcnt(7)
	v_add_f32_e32 v1, v1, v4
	s_waitcnt vmcnt(6)
	v_add_f32_e32 v1, v1, v5
	s_waitcnt vmcnt(5)
	v_add_f32_e32 v1, v1, v6
	s_waitcnt vmcnt(4)
	v_add_f32_e32 v1, v1, v7
	s_waitcnt vmcnt(3)
	v_add_f32_e32 v1, v1, v8
	s_waitcnt vmcnt(2)
	v_add_f32_e32 v1, v1, v9
	s_waitcnt vmcnt(1)
	v_add_f32_e32 v1, v1, v10
	s_waitcnt vmcnt(0)
	v_add_f32_e32 v1, v1, v2
	v_fmac_f32_e32 v3, 0x3a800000, v1
	v_mul_f32_e32 v1, 0x4f800000, v3
	v_cmp_gt_f32_e32 vcc, s0, v3
	s_nop 1
	v_cndmask_b32_e32 v1, v3, v1, vcc
	v_sqrt_f32_e32 v2, v1
	v_mov_b32_e32 v3, 0x260
	v_add_u32_e32 v4, -1, v2
	v_add_u32_e32 v5, 1, v2
	v_fma_f32 v6, -v4, v2, v1
	v_fma_f32 v7, -v5, v2, v1
	v_cmp_ge_f32_e64 s[0:1], 0, v6
	s_nop 1
	v_cndmask_b32_e64 v2, v2, v4, s[0:1]
	v_cmp_lt_f32_e64 s[0:1], 0, v7
	s_nop 1
	v_cndmask_b32_e64 v2, v2, v5, s[0:1]
	v_mul_f32_e32 v4, 0x37800000, v2
	v_cndmask_b32_e32 v2, v2, v4, vcc
	v_cmp_class_f32_e32 vcc, v1, v3
	s_nop 1
	v_cndmask_b32_e32 v1, v2, v1, vcc
	v_div_scale_f32 v2, s[0:1], v1, v1, 1.0
	v_rcp_f32_e32 v3, v2
	v_div_scale_f32 v4, vcc, 1.0, v1, 1.0
	v_fma_f32 v5, -v2, v3, 1.0
	v_fmac_f32_e32 v3, v5, v3
	v_mul_f32_e32 v5, v4, v3
	v_fma_f32 v6, -v2, v5, v4
	v_fmac_f32_e32 v5, v6, v3
	v_fma_f32 v2, -v2, v5, v4
	v_div_fmas_f32 v2, v2, v3, v5
	v_div_fixup_f32 v1, v2, v1, 1.0
	ds_write_b32 v0, v1

.LBB0_793:
	s_add_u32 s8, s28, 0x5c00000
	s_movk_i32 s0, 0x100
	s_addc_u32 s9, s29, 0
	v_cmp_gt_u32_e64 s[4:5], s0, v197
	s_add_i32 s0, 0, 0x20000
	s_cmp_gt_i32 s47, -1
	v_lshl_add_u32 v0, v197, 2, s0
	s_cselect_b64 s[0:1], -1, 0
	s_and_b64 s[0:1], s[0:1], s[4:5]
	s_cmp_gt_i32 s49, -1
	s_cselect_b64 s[10:11], -1, 0
	s_andn2_b64 s[10:11], s[10:11], s[4:5]
	s_or_b64 s[0:1], s[0:1], s[10:11]
	s_waitcnt vmcnt(0)
	s_barrier
	s_and_saveexec_b64 s[10:11], s[0:1]
	s_cbranch_execz .LBB0_795
	v_mov_b32_e32 v30, s47
	v_mov_b32_e32 v31, s49
	v_cmp_lt_u32_e32 vcc, 0xff, v197
	v_and_b32_e32 v2, 0xff, v197
	s_nop 0
	v_cndmask_b32_e32 v30, v30, v31, vcc
	v_lshl_or_b32 v2, v30, 8, v2
	v_mov_b32_e32 v3, 0
	v_lshl_add_u64 v[4:5], v[2:3], 2, s[8:9]
	v_add_u32_e32 v6, 0x8000, v2
	v_mov_b32_e32 v7, v3
	v_add_u32_e32 v8, 0x10000, v2
	v_mov_b32_e32 v9, v3
	v_add_u32_e32 v10, 0x18000, v2
	v_mov_b32_e32 v11, v3
	v_add_u32_e32 v12, 0x20000, v2
	v_mov_b32_e32 v13, v3
	v_add_u32_e32 v14, 0x28000, v2
	v_mov_b32_e32 v15, v3
	v_add_u32_e32 v16, 0x30000, v2
	v_mov_b32_e32 v17, v3
	v_add_u32_e32 v18, 0x38000, v2
	v_mov_b32_e32 v19, v3
	v_lshl_add_u64 v[6:7], v[6:7], 2, s[8:9]
	v_lshl_add_u64 v[8:9], v[8:9], 2, s[8:9]
	v_lshl_add_u64 v[10:11], v[10:11], 2, s[8:9]
	v_lshl_add_u64 v[12:13], v[12:13], 2, s[8:9]
	v_lshl_add_u64 v[14:15], v[14:15], 2, s[8:9]
	v_lshl_add_u64 v[16:17], v[16:17], 2, s[8:9]
	v_lshl_add_u64 v[18:19], v[18:19], 2, s[8:9]
	global_load_dword v1, v[4:5], off
	global_load_dword v20, v[6:7], off
	global_load_dword v21, v[8:9], off
	global_load_dword v22, v[10:11], off
	global_load_dword v23, v[12:13], off
	global_load_dword v24, v[14:15], off
	global_load_dword v25, v[16:17], off
	global_load_dword v26, v[18:19], off
	v_add_u32_e32 v4, 0x40000, v2
	v_mov_b32_e32 v5, v3
	v_lshl_add_u64 v[4:5], v[4:5], 2, s[8:9]
	v_add_u32_e32 v6, 0x48000, v2
	v_mov_b32_e32 v7, v3
	v_add_u32_e32 v8, 0x50000, v2
	v_mov_b32_e32 v9, v3
	v_add_u32_e32 v10, 0x58000, v2
	v_mov_b32_e32 v11, v3
	v_add_u32_e32 v12, 0x60000, v2
	v_mov_b32_e32 v13, v3
	v_add_u32_e32 v14, 0x68000, v2
	v_mov_b32_e32 v15, v3
	v_add_u32_e32 v16, 0x70000, v2
	v_mov_b32_e32 v17, v3
	v_add_u32_e32 v2, 0x78000, v2
	v_lshl_add_u64 v[6:7], v[6:7], 2, s[8:9]
	v_lshl_add_u64 v[8:9], v[8:9], 2, s[8:9]
	v_lshl_add_u64 v[10:11], v[10:11], 2, s[8:9]
	v_lshl_add_u64 v[12:13], v[12:13], 2, s[8:9]
	v_lshl_add_u64 v[14:15], v[14:15], 2, s[8:9]
	v_lshl_add_u64 v[16:17], v[16:17], 2, s[8:9]
	v_lshl_add_u64 v[2:3], v[2:3], 2, s[8:9]
	global_load_dword v18, v[4:5], off
	global_load_dword v19, v[6:7], off
	global_load_dword v27, v[8:9], off
	global_load_dword v28, v[10:11], off
	global_load_dword v29, v[12:13], off
	global_load_dword v30, v[14:15], off
	global_load_dword v31, v[16:17], off
	global_load_dword v32, v[2:3], off
	v_mov_b32_e32 v2, 0x358637bd
	s_mov_b32 s0, 0xf800000
	v_mov_b32_e32 v3, 0x260
	s_waitcnt vmcnt(15)
	v_add_f32_e32 v1, 0, v1
	s_waitcnt vmcnt(14)
	v_add_f32_e32 v1, v1, v20
	s_waitcnt vmcnt(13)
	v_add_f32_e32 v1, v1, v21
	s_waitcnt vmcnt(12)
	v_add_f32_e32 v1, v1, v22
	s_waitcnt vmcnt(11)
	v_add_f32_e32 v1, v1, v23
	s_waitcnt vmcnt(10)
	v_add_f32_e32 v1, v1, v24
	s_waitcnt vmcnt(9)
	v_add_f32_e32 v1, v1, v25
	s_waitcnt vmcnt(8)
	v_add_f32_e32 v1, v1, v26
	s_waitcnt vmcnt(7)
	v_add_f32_e32 v1, v1, v18
	s_waitcnt vmcnt(6)
	v_add_f32_e32 v1, v1, v19
	s_waitcnt vmcnt(5)
	v_add_f32_e32 v1, v1, v27
	s_waitcnt vmcnt(4)
	v_add_f32_e32 v1, v1, v28
	s_waitcnt vmcnt(3)
	v_add_f32_e32 v1, v1, v29
	s_waitcnt vmcnt(2)
	v_add_f32_e32 v1, v1, v30
	s_waitcnt vmcnt(1)
	v_add_f32_e32 v1, v1, v31
	s_waitcnt vmcnt(0)
	v_add_f32_e32 v1, v1, v32
	v_fmac_f32_e32 v2, 0x3a800000, v1
	v_mul_f32_e32 v1, 0x4f800000, v2
	v_cmp_gt_f32_e32 vcc, s0, v2
	s_nop 1
	v_cndmask_b32_e32 v1, v2, v1, vcc
	v_sqrt_f32_e32 v2, v1
	s_nop 0
	v_add_u32_e32 v4, -1, v2
	v_add_u32_e32 v5, 1, v2
	v_fma_f32 v6, -v4, v2, v1
	v_fma_f32 v7, -v5, v2, v1
	v_cmp_ge_f32_e64 s[0:1], 0, v6
	s_nop 1
	v_cndmask_b32_e64 v2, v2, v4, s[0:1]
	v_cmp_lt_f32_e64 s[0:1], 0, v7
	s_nop 1
	v_cndmask_b32_e64 v2, v2, v5, s[0:1]
	v_mul_f32_e32 v4, 0x37800000, v2
	v_cndmask_b32_e32 v2, v2, v4, vcc
	v_cmp_class_f32_e32 vcc, v1, v3
	s_nop 1
	v_cndmask_b32_e32 v1, v2, v1, vcc
	v_div_scale_f32 v2, s[0:1], v1, v1, 1.0
	v_rcp_f32_e32 v3, v2
	v_div_scale_f32 v4, vcc, 1.0, v1, 1.0
	v_fma_f32 v5, -v2, v3, 1.0
	v_fmac_f32_e32 v3, v5, v3
	v_mul_f32_e32 v5, v4, v3
	v_fma_f32 v6, -v2, v5, v4
	v_fmac_f32_e32 v5, v6, v3
	v_fma_f32 v2, -v2, v5, v4
	v_div_fmas_f32 v2, v2, v3, v5
	v_div_fixup_f32 v1, v2, v1, 1.0
	ds_write_b32 v0, v1

.LBB0_983:
	s_add_u32 s8, s28, 0x5e00000
	s_movk_i32 s0, 0x100
	s_addc_u32 s9, s29, 0
	v_cmp_gt_u32_e64 s[4:5], s0, v197
	s_add_i32 s0, 0, 0x20000
	s_cmp_gt_i32 s47, -1
	v_lshl_add_u32 v0, v197, 2, s0
	s_cselect_b64 s[0:1], -1, 0
	s_and_b64 s[0:1], s[0:1], s[4:5]
	s_cmp_gt_i32 s49, -1
	s_cselect_b64 s[10:11], -1, 0
	s_andn2_b64 s[10:11], s[10:11], s[4:5]
	s_or_b64 s[0:1], s[0:1], s[10:11]
	s_waitcnt vmcnt(0)
	s_barrier
	s_and_saveexec_b64 s[10:11], s[0:1]
	s_cbranch_execz .LBB0_985
	v_mov_b32_e32 v30, s47
	v_mov_b32_e32 v31, s49
	v_cmp_lt_u32_e32 vcc, 0xff, v197
	v_and_b32_e32 v2, 0xff, v197
	s_nop 0
	v_cndmask_b32_e32 v30, v30, v31, vcc
	v_lshl_or_b32 v2, v30, 8, v2
	v_mov_b32_e32 v3, 0
	v_lshl_add_u64 v[4:5], v[2:3], 2, s[8:9]
	v_add_u32_e32 v6, 0x8000, v2
	v_mov_b32_e32 v7, v3
	v_add_u32_e32 v8, 0x10000, v2
	v_mov_b32_e32 v9, v3
	v_add_u32_e32 v10, 0x18000, v2
	v_mov_b32_e32 v11, v3
	v_add_u32_e32 v12, 0x20000, v2
	v_mov_b32_e32 v13, v3
	v_add_u32_e32 v14, 0x28000, v2
	v_mov_b32_e32 v15, v3
	v_add_u32_e32 v16, 0x30000, v2
	v_mov_b32_e32 v17, v3
	v_add_u32_e32 v18, 0x38000, v2
	v_mov_b32_e32 v19, v3
	v_lshl_add_u64 v[6:7], v[6:7], 2, s[8:9]
	v_lshl_add_u64 v[8:9], v[8:9], 2, s[8:9]
	v_lshl_add_u64 v[10:11], v[10:11], 2, s[8:9]
	v_lshl_add_u64 v[12:13], v[12:13], 2, s[8:9]
	v_lshl_add_u64 v[14:15], v[14:15], 2, s[8:9]
	v_lshl_add_u64 v[16:17], v[16:17], 2, s[8:9]
	v_lshl_add_u64 v[18:19], v[18:19], 2, s[8:9]
	global_load_dword v1, v[4:5], off
	global_load_dword v20, v[6:7], off
	global_load_dword v21, v[8:9], off
	global_load_dword v22, v[10:11], off
	global_load_dword v23, v[12:13], off
	global_load_dword v24, v[14:15], off
	global_load_dword v25, v[16:17], off
	global_load_dword v26, v[18:19], off
	v_add_u32_e32 v4, 0x40000, v2
	v_mov_b32_e32 v5, v3
	v_lshl_add_u64 v[4:5], v[4:5], 2, s[8:9]
	v_add_u32_e32 v6, 0x48000, v2
	v_mov_b32_e32 v7, v3
	v_add_u32_e32 v8, 0x50000, v2
	v_mov_b32_e32 v9, v3
	v_add_u32_e32 v10, 0x58000, v2
	v_mov_b32_e32 v11, v3
	v_add_u32_e32 v12, 0x60000, v2
	v_mov_b32_e32 v13, v3
	v_add_u32_e32 v14, 0x68000, v2
	v_mov_b32_e32 v15, v3
	v_add_u32_e32 v16, 0x70000, v2
	v_mov_b32_e32 v17, v3
	v_add_u32_e32 v2, 0x78000, v2
	v_lshl_add_u64 v[6:7], v[6:7], 2, s[8:9]
	v_lshl_add_u64 v[8:9], v[8:9], 2, s[8:9]
	v_lshl_add_u64 v[10:11], v[10:11], 2, s[8:9]
	v_lshl_add_u64 v[12:13], v[12:13], 2, s[8:9]
	v_lshl_add_u64 v[14:15], v[14:15], 2, s[8:9]
	v_lshl_add_u64 v[16:17], v[16:17], 2, s[8:9]
	v_lshl_add_u64 v[2:3], v[2:3], 2, s[8:9]
	global_load_dword v18, v[4:5], off
	global_load_dword v19, v[6:7], off
	global_load_dword v27, v[8:9], off
	global_load_dword v28, v[10:11], off
	global_load_dword v29, v[12:13], off
	global_load_dword v30, v[14:15], off
	global_load_dword v31, v[16:17], off
	global_load_dword v32, v[2:3], off
	v_mov_b32_e32 v2, 0x358637bd
	s_mov_b32 s0, 0xf800000
	v_mov_b32_e32 v3, 0x260
	s_waitcnt vmcnt(15)
	v_add_f32_e32 v1, 0, v1
	s_waitcnt vmcnt(14)
	v_add_f32_e32 v1, v1, v20
	s_waitcnt vmcnt(13)
	v_add_f32_e32 v1, v1, v21
	s_waitcnt vmcnt(12)
	v_add_f32_e32 v1, v1, v22
	s_waitcnt vmcnt(11)
	v_add_f32_e32 v1, v1, v23
	s_waitcnt vmcnt(10)
	v_add_f32_e32 v1, v1, v24
	s_waitcnt vmcnt(9)
	v_add_f32_e32 v1, v1, v25
	s_waitcnt vmcnt(8)
	v_add_f32_e32 v1, v1, v26
	s_waitcnt vmcnt(7)
	v_add_f32_e32 v1, v1, v18
	s_waitcnt vmcnt(6)
	v_add_f32_e32 v1, v1, v19
	s_waitcnt vmcnt(5)
	v_add_f32_e32 v1, v1, v27
	s_waitcnt vmcnt(4)
	v_add_f32_e32 v1, v1, v28
	s_waitcnt vmcnt(3)
	v_add_f32_e32 v1, v1, v29
	s_waitcnt vmcnt(2)
	v_add_f32_e32 v1, v1, v30
	s_waitcnt vmcnt(1)
	v_add_f32_e32 v1, v1, v31
	s_waitcnt vmcnt(0)
	v_add_f32_e32 v1, v1, v32
	v_fmac_f32_e32 v2, 0x3a800000, v1
	v_mul_f32_e32 v1, 0x4f800000, v2
	v_cmp_gt_f32_e32 vcc, s0, v2
	s_nop 1
	v_cndmask_b32_e32 v1, v2, v1, vcc
	v_sqrt_f32_e32 v2, v1
	s_nop 0
	v_add_u32_e32 v4, -1, v2
	v_add_u32_e32 v5, 1, v2
	v_fma_f32 v6, -v4, v2, v1
	v_fma_f32 v7, -v5, v2, v1
	v_cmp_ge_f32_e64 s[0:1], 0, v6
	s_nop 1
	v_cndmask_b32_e64 v2, v2, v4, s[0:1]
	v_cmp_lt_f32_e64 s[0:1], 0, v7
	s_nop 1
	v_cndmask_b32_e64 v2, v2, v5, s[0:1]
	v_mul_f32_e32 v4, 0x37800000, v2
	v_cndmask_b32_e32 v2, v2, v4, vcc
	v_cmp_class_f32_e32 vcc, v1, v3
	s_nop 1
	v_cndmask_b32_e32 v1, v2, v1, vcc
	v_div_scale_f32 v2, s[0:1], v1, v1, 1.0
	v_rcp_f32_e32 v3, v2
	v_div_scale_f32 v4, vcc, 1.0, v1, 1.0
	v_fma_f32 v5, -v2, v3, 1.0
	v_fmac_f32_e32 v3, v5, v3
	v_mul_f32_e32 v5, v4, v3
	v_fma_f32 v6, -v2, v5, v4
	v_fmac_f32_e32 v5, v6, v3
	v_fma_f32 v2, -v2, v5, v4
	v_div_fmas_f32 v2, v2, v3, v5
	v_div_fixup_f32 v1, v2, v1, 1.0
	ds_write_b32 v0, v1

.LBB0_1723:
	s_add_u32 s8, s28, 0x6200000
	s_movk_i32 s0, 0x100
	s_addc_u32 s9, s29, 0
	v_cmp_gt_u32_e64 s[4:5], s0, v197
	s_add_i32 s0, 0, 0x20000
	s_cmp_gt_i32 s47, -1
	v_lshl_add_u32 v0, v197, 2, s0
	s_cselect_b64 s[0:1], -1, 0
	s_and_b64 s[0:1], s[0:1], s[4:5]
	s_cmp_gt_i32 s46, -1
	s_cselect_b64 s[10:11], -1, 0
	s_andn2_b64 s[10:11], s[10:11], s[4:5]
	s_or_b64 s[0:1], s[0:1], s[10:11]
	s_waitcnt vmcnt(0)
	s_barrier
	s_and_saveexec_b64 s[10:11], s[0:1]
	s_cbranch_execz .LBB0_1725
	v_mov_b32_e32 v30, s47
	v_mov_b32_e32 v31, s46
	v_cmp_lt_u32_e32 vcc, 0xff, v197
	v_and_b32_e32 v2, 0xff, v197
	s_nop 0
	v_cndmask_b32_e32 v30, v30, v31, vcc
	v_lshl_or_b32 v2, v30, 8, v2
	v_mov_b32_e32 v3, 0
	v_lshl_add_u64 v[4:5], v[2:3], 2, s[8:9]
	v_add_u32_e32 v6, 0x8000, v2
	v_mov_b32_e32 v7, v3
	v_add_u32_e32 v8, 0x10000, v2
	v_mov_b32_e32 v9, v3
	v_add_u32_e32 v10, 0x18000, v2
	v_mov_b32_e32 v11, v3
	v_add_u32_e32 v12, 0x20000, v2
	v_mov_b32_e32 v13, v3
	v_add_u32_e32 v14, 0x28000, v2
	v_mov_b32_e32 v15, v3
	v_add_u32_e32 v16, 0x30000, v2
	v_mov_b32_e32 v17, v3
	v_add_u32_e32 v18, 0x38000, v2
	v_mov_b32_e32 v19, v3
	v_lshl_add_u64 v[6:7], v[6:7], 2, s[8:9]
	v_lshl_add_u64 v[8:9], v[8:9], 2, s[8:9]
	v_lshl_add_u64 v[10:11], v[10:11], 2, s[8:9]
	v_lshl_add_u64 v[12:13], v[12:13], 2, s[8:9]
	v_lshl_add_u64 v[14:15], v[14:15], 2, s[8:9]
	v_lshl_add_u64 v[16:17], v[16:17], 2, s[8:9]
	v_lshl_add_u64 v[18:19], v[18:19], 2, s[8:9]
	global_load_dword v1, v[4:5], off
	global_load_dword v20, v[6:7], off
	global_load_dword v21, v[8:9], off
	global_load_dword v22, v[10:11], off
	global_load_dword v23, v[12:13], off
	global_load_dword v24, v[14:15], off
	global_load_dword v25, v[16:17], off
	global_load_dword v26, v[18:19], off
	v_add_u32_e32 v4, 0x40000, v2
	v_mov_b32_e32 v5, v3
	v_lshl_add_u64 v[4:5], v[4:5], 2, s[8:9]
	v_add_u32_e32 v6, 0x48000, v2
	v_mov_b32_e32 v7, v3
	v_add_u32_e32 v8, 0x50000, v2
	v_mov_b32_e32 v9, v3
	v_add_u32_e32 v10, 0x58000, v2
	v_mov_b32_e32 v11, v3
	v_add_u32_e32 v12, 0x60000, v2
	v_mov_b32_e32 v13, v3
	v_add_u32_e32 v14, 0x68000, v2
	v_mov_b32_e32 v15, v3
	v_add_u32_e32 v16, 0x70000, v2
	v_mov_b32_e32 v17, v3
	v_add_u32_e32 v2, 0x78000, v2
	v_lshl_add_u64 v[6:7], v[6:7], 2, s[8:9]
	v_lshl_add_u64 v[8:9], v[8:9], 2, s[8:9]
	v_lshl_add_u64 v[10:11], v[10:11], 2, s[8:9]
	v_lshl_add_u64 v[12:13], v[12:13], 2, s[8:9]
	v_lshl_add_u64 v[14:15], v[14:15], 2, s[8:9]
	v_lshl_add_u64 v[16:17], v[16:17], 2, s[8:9]
	v_lshl_add_u64 v[2:3], v[2:3], 2, s[8:9]
	global_load_dword v18, v[4:5], off
	global_load_dword v19, v[6:7], off
	global_load_dword v27, v[8:9], off
	global_load_dword v28, v[10:11], off
	global_load_dword v29, v[12:13], off
	global_load_dword v30, v[14:15], off
	global_load_dword v31, v[16:17], off
	global_load_dword v32, v[2:3], off
	v_mov_b32_e32 v2, 0x358637bd
	s_mov_b32 s0, 0xf800000
	v_mov_b32_e32 v3, 0x260
	s_waitcnt vmcnt(15)
	v_add_f32_e32 v1, 0, v1
	s_waitcnt vmcnt(14)
	v_add_f32_e32 v1, v1, v20
	s_waitcnt vmcnt(13)
	v_add_f32_e32 v1, v1, v21
	s_waitcnt vmcnt(12)
	v_add_f32_e32 v1, v1, v22
	s_waitcnt vmcnt(11)
	v_add_f32_e32 v1, v1, v23
	s_waitcnt vmcnt(10)
	v_add_f32_e32 v1, v1, v24
	s_waitcnt vmcnt(9)
	v_add_f32_e32 v1, v1, v25
	s_waitcnt vmcnt(8)
	v_add_f32_e32 v1, v1, v26
	s_waitcnt vmcnt(7)
	v_add_f32_e32 v1, v1, v18
	s_waitcnt vmcnt(6)
	v_add_f32_e32 v1, v1, v19
	s_waitcnt vmcnt(5)
	v_add_f32_e32 v1, v1, v27
	s_waitcnt vmcnt(4)
	v_add_f32_e32 v1, v1, v28
	s_waitcnt vmcnt(3)
	v_add_f32_e32 v1, v1, v29
	s_waitcnt vmcnt(2)
	v_add_f32_e32 v1, v1, v30
	s_waitcnt vmcnt(1)
	v_add_f32_e32 v1, v1, v31
	s_waitcnt vmcnt(0)
	v_add_f32_e32 v1, v1, v32
	v_fmac_f32_e32 v2, 0x3a800000, v1
	v_mul_f32_e32 v1, 0x4f800000, v2
	v_cmp_gt_f32_e32 vcc, s0, v2
	s_nop 1
	v_cndmask_b32_e32 v1, v2, v1, vcc
	v_sqrt_f32_e32 v2, v1
	s_nop 0
	v_add_u32_e32 v4, -1, v2
	v_add_u32_e32 v5, 1, v2
	v_fma_f32 v6, -v4, v2, v1
	v_fma_f32 v7, -v5, v2, v1
	v_cmp_ge_f32_e64 s[0:1], 0, v6
	s_nop 1
	v_cndmask_b32_e64 v2, v2, v4, s[0:1]
	v_cmp_lt_f32_e64 s[0:1], 0, v7
	s_nop 1
	v_cndmask_b32_e64 v2, v2, v5, s[0:1]
	v_mul_f32_e32 v4, 0x37800000, v2
	v_cndmask_b32_e32 v2, v2, v4, vcc
	v_cmp_class_f32_e32 vcc, v1, v3
	s_nop 1
	v_cndmask_b32_e32 v1, v2, v1, vcc
	v_div_scale_f32 v2, s[0:1], v1, v1, 1.0
	v_rcp_f32_e32 v3, v2
	v_div_scale_f32 v4, vcc, 1.0, v1, 1.0
	v_fma_f32 v5, -v2, v3, 1.0
	v_fmac_f32_e32 v3, v5, v3
	v_mul_f32_e32 v5, v4, v3
	v_fma_f32 v6, -v2, v5, v4
	v_fmac_f32_e32 v5, v6, v3
	v_fma_f32 v2, -v2, v5, v4
	v_div_fmas_f32 v2, v2, v3, v5
	v_div_fixup_f32 v1, v2, v1, 1.0
	ds_write_b32 v0, v1
